# combo + HGRN2 state pass: loop-top waits relaxed to vmcnt(8) (no wait for the previous unit's eight state-store acknowledgements)
# speedup vs baseline: 1.0053x; 1.0053x over previous
.LBB0_208:
	s_andn2_b64 vcc, exec, s[6:7]
	s_cbranch_vccnz .LBB0_232
	v_readlane_b32 s6, v252, 8
	s_waitcnt vmcnt(0)
	v_mov_b32_e32 v18, v204
	v_readlane_b32 s7, v252, 9
	s_andn2_b64 vcc, exec, s[6:7]
	v_readfirstlane_b32 s8, v18
	s_cbranch_vccnz .LBB0_232
	s_add_u32 s6, s30, 0xec00000
	s_addc_u32 s7, s31, 0
	s_add_u32 s10, s30, 0x16c00000
	s_addc_u32 s11, s31, 0
	s_ashr_i32 s22, s8, 6
	s_lshl_b32 s34, s22, 3
	s_ashr_i32 s35, s34, 31
	v_readlane_b32 s16, v252, 11
	s_add_u32 s12, s16, s34
	v_readlane_b32 s17, v252, 12
	v_readlane_b32 s0, v252, 13
	s_addc_u32 s13, s17, s35
	s_lshl_b32 s0, s0, 1
	v_and_b32_e32 v19, 63, v18
	s_add_u32 s14, s10, s0
	s_addc_u32 s15, s11, 0
	v_lshlrev_b32_e32 v0, 2, v19
	v_lshl_add_u64 v[2:3], s[14:15], 0, v[0:1]
	s_lshl_b64 s[12:13], s[12:13], 11
	v_lshl_add_u64 v[2:3], v[2:3], 0, s[12:13]
	s_movk_i32 s9, 0x1000
	v_add_co_u32_e32 v4, vcc, s9, v2
	s_movk_i32 s9, 0x2000
	s_nop 0
	v_addc_co_u32_e32 v5, vcc, 0, v3, vcc
	v_add_co_u32_e32 v6, vcc, s9, v2
	s_movk_i32 s9, 0x3000
	s_nop 0
	v_addc_co_u32_e32 v7, vcc, 0, v3, vcc
	global_load_dword v58, v[6:7], off offset:-4096
	global_load_dword v60, v[6:7], off
	global_load_dword v61, v[6:7], off offset:2048
	v_add_co_u32_e32 v6, vcc, s9, v2
	s_movk_i32 s12, 0x90
	s_nop 0
	v_addc_co_u32_e32 v7, vcc, 0, v3, vcc
	global_load_dword v62, v[2:3], off
	global_load_dword v63, v[2:3], off offset:2048
	global_load_dword v64, v[4:5], off offset:2048
	global_load_dword v65, v[6:7], off
	global_load_dword v66, v[6:7], off offset:2048
	v_lshlrev_b32_e32 v2, 1, v18
	v_and_b32_e32 v10, 62, v2
	v_or_b32_e32 v2, s16, v10
	v_mov_b32_e32 v3, s17
	v_ashrrev_i32_e32 v4, 2, v18
	v_lshlrev_b64 v[2:3], 11, v[2:3]
	v_and_b32_e32 v12, -8, v4
	v_lshl_add_u64 v[2:3], s[6:7], 0, v[2:3]
	v_ashrrev_i32_e32 v13, 31, v12
	v_lshl_add_u64 v[2:3], v[2:3], 0, s[0:1]
	v_lshl_add_u64 v[6:7], v[12:13], 1, v[2:3]
	global_load_dwordx4 v[2:5], v[6:7], off
	s_nop 0
	global_load_dwordx4 v[6:9], v[6:7], off offset:2048
	s_lshl_b32 s0, s22, 9
	s_add_i32 s0, s0, 0
	v_mul_lo_u32 v11, v12, s12
	s_cmp_gt_u32 s8, 63
	v_and_b32_e32 v20, 15, v18
	v_add_u32_e32 v21, 0, v11
	v_lshlrev_b32_e32 v11, 2, v18
	v_lshlrev_b32_e32 v16, 3, v19
	s_cselect_b64 s[8:9], -1, 0
	v_mov_b32_e32 v17, v1
	s_lshl_b32 s24, s22, 4
	v_and_b32_e32 v22, 0x7c, v11
	v_add_u32_e32 v11, s0, v16
	v_lshl_add_u64 v[14:15], s[10:11], 0, v[0:1]
	v_add_u32_e32 v59, 0, v16
	v_lshl_add_u64 v[16:17], s[30:31], 0, v[16:17]
	s_mov_b64 s[10:11], 0x1ec00000
	s_ashr_i32 s25, s24, 31
	v_or_b32_e32 v0, s24, v20
	v_lshl_add_u64 v[16:17], v[16:17], 0, s[10:11]
	v_mul_lo_u32 v0, v0, s12
	s_lshl_b64 s[10:11], s[24:25], 1
	v_readlane_b32 s12, v254, 8
	v_readlane_b32 s13, v254, 9
	s_add_u32 s10, s12, s10
	v_add_u32_e32 v24, 0, v0
	s_addc_u32 s11, s13, s11
	v_lshrrev_b32_e32 v0, 1, v18
	s_movk_i32 s0, 0x118
	v_and_b32_e32 v0, 24, v0
	s_cmp_lt_i32 s22, 1
	v_mad_u32_u24 v23, v19, s0, v59
	v_and_b32_e32 v25, 48, v18
	v_lshl_add_u64 v[18:19], s[10:11], 0, v[0:1]
	s_cselect_b64 s[10:11], -1, 0
	s_cmp_lt_i32 s22, 2
	s_cselect_b64 s[12:13], -1, 0
	s_cmp_lt_i32 s22, 3
	s_cselect_b64 s[14:15], -1, 0
	s_cmp_lt_i32 s22, 4
	s_cselect_b64 s[16:17], -1, 0
	s_cmp_lt_i32 s22, 5
	s_cselect_b64 s[18:19], -1, 0
	s_cmp_lt_i32 s22, 6
	v_add_u32_e32 v26, 0, v25
	s_cselect_b64 s[20:21], -1, 0
	s_cmp_lt_i32 s22, 7
	v_mul_u32_u24_e32 v27, 0x90, v20
	v_lshlrev_b32_e32 v0, 8, v20
	s_cselect_b64 s[22:23], -1, 0
	v_lshl_add_u64 v[18:19], v[18:19], 0, v[0:1]
	v_add_u32_e32 v67, v21, v22
	v_add_u32_e32 v68, s24, v23
	v_add_u32_e32 v69, v24, v25
	v_add_u32_e32 v70, v26, v27
	s_mov_b32 s100, 0x5800
	v_readlane_b32 s38, v252, 10
	s_mov_b32 s28, s2
	s_waitcnt vmcnt(0)
	s_branch .LBB0_212

.LBB0_212:
	s_waitcnt vmcnt(8)
	v_and_b32_e32 v0, 0xffff, v2
	v_lshrrev_b32_e32 v20, 16, v2
	s_mov_b32 s0, 0xffff0000
	v_lshlrev_b32_e32 v50, 16, v62
	v_and_b32_e32 v51, 0xffff0000, v62
	s_waitcnt vmcnt(8)
	v_lshl_or_b32 v0, v6, 16, v0
	v_and_or_b32 v20, v6, s0, v20
	v_add_u32_e32 v21, 0x4800, v67
	v_and_b32_e32 v49, 0xffff0000, v63
	v_lshlrev_b32_e32 v48, 16, v63
	v_pk_add_f32 v[34:35], v[50:51], 0 op_sel_hi:[1,0]
	ds_write2_b32 v21, v0, v20 offset1:36
	v_and_b32_e32 v0, 0xffff, v3
	v_lshrrev_b32_e32 v20, 16, v3
	v_and_b32_e32 v47, 0xffff0000, v58
	v_lshlrev_b32_e32 v46, 16, v58
	v_pk_add_f32 v[32:33], v[34:35], v[48:49]
	v_lshl_or_b32 v0, v7, 16, v0
	v_and_or_b32 v20, v7, s0, v20
	v_and_b32_e32 v45, 0xffff0000, v64
	v_lshlrev_b32_e32 v44, 16, v64
	v_pk_add_f32 v[30:31], v[32:33], v[46:47]
	ds_write2_b32 v21, v0, v20 offset0:72 offset1:108
	v_and_b32_e32 v0, 0xffff, v4
	v_lshrrev_b32_e32 v20, 16, v4
	v_and_b32_e32 v43, 0xffff0000, v60
	v_lshlrev_b32_e32 v42, 16, v60
	v_pk_add_f32 v[28:29], v[30:31], v[44:45]
	v_lshl_or_b32 v0, v8, 16, v0
	v_and_or_b32 v20, v8, s0, v20
	v_and_b32_e32 v41, 0xffff0000, v61
	v_lshlrev_b32_e32 v40, 16, v61
	v_pk_add_f32 v[26:27], v[28:29], v[42:43]
	s_add_i32 s39, s28, s46
	ds_write2_b32 v21, v0, v20 offset0:144 offset1:180
	v_and_b32_e32 v0, 0xffff, v5
	v_lshrrev_b32_e32 v20, 16, v5
	v_and_b32_e32 v39, 0xffff0000, v65
	v_lshlrev_b32_e32 v38, 16, v65
	v_pk_add_f32 v[24:25], v[26:27], v[40:41]
	s_cmpk_gt_i32 s39, 0xfff
	v_lshl_or_b32 v0, v9, 16, v0
	v_and_or_b32 v20, v9, s0, v20
	v_and_b32_e32 v37, 0xffff0000, v66
	v_lshlrev_b32_e32 v36, 16, v66
	v_pk_add_f32 v[22:23], v[24:25], v[38:39]
	s_cselect_b64 s[24:25], -1, 0
	ds_write2_b32 v21, v0, v20 offset0:216 offset1:252
	v_pk_add_f32 v[20:21], v[22:23], v[36:37]
	s_and_b64 vcc, exec, s[24:25]
	ds_write_b64 v11, v[20:21] offset:36864
	s_cbranch_vccnz .LBB0_214
	v_readlane_b32 s0, v252, 56
	s_add_i32 s0, s0, s38
	s_and_b32 s0, s0, 0xf00
	s_ashr_i32 s29, s39, 4
	s_add_i32 s0, s0, s29
	s_ashr_i32 s29, s0, 31
	s_lshr_b32 s29, s29, 24
	s_add_i32 s29, s0, s29
	s_and_b32 s36, s29, 0xffffff00
	s_sub_i32 s36, s0, s36
	s_ashr_i32 s40, s29, 11
	s_ashr_i32 s41, s40, 31
	s_ashr_i32 s37, s36, 31
	s_lshl_b64 s[40:41], s[40:41], 14
	s_lshl_b64 s[36:37], s[36:37], 6
	s_add_u32 s40, s40, s36
	s_addc_u32 s41, s41, s37
	s_add_u32 s36, s40, s34
	s_addc_u32 s37, s41, s35
	s_and_b32 s0, s29, 0x700
	v_lshl_add_u64 v[2:3], v[14:15], 0, s[0:1]
	s_lshl_b64 s[36:37], s[36:37], 11
	v_lshl_add_u64 v[2:3], v[2:3], 0, s[36:37]
	s_movk_i32 s29, 0x1000
	v_add_co_u32_e32 v4, vcc, s29, v2
	s_movk_i32 s29, 0x2000
	s_nop 0
	v_addc_co_u32_e32 v5, vcc, 0, v3, vcc
	v_add_co_u32_e32 v6, vcc, s29, v2
	s_movk_i32 s29, 0x3000
	s_nop 0
	v_addc_co_u32_e32 v7, vcc, 0, v3, vcc
	global_load_dword v58, v[6:7], off offset:-4096
	global_load_dword v60, v[6:7], off
	global_load_dword v61, v[6:7], off offset:2048
	v_add_co_u32_e32 v6, vcc, s29, v2
	s_nop 1
	v_addc_co_u32_e32 v7, vcc, 0, v3, vcc
	global_load_dword v62, v[2:3], off
	global_load_dword v63, v[2:3], off offset:2048
	global_load_dword v64, v[4:5], off offset:2048
	global_load_dword v65, v[6:7], off
	global_load_dword v66, v[6:7], off offset:2048
	v_mov_b32_e32 v3, s41
	v_or_b32_e32 v2, s40, v10
	v_lshlrev_b64 v[2:3], 11, v[2:3]
	v_lshl_add_u64 v[2:3], s[6:7], 0, v[2:3]
	v_lshl_add_u64 v[2:3], v[2:3], 0, s[0:1]
	v_lshl_add_u64 v[6:7], v[12:13], 1, v[2:3]
	global_load_dwordx4 v[2:5], v[6:7], off
	s_nop 0
	global_load_dwordx4 v[6:9], v[6:7], off offset:2048
